# removed the redundant back-to-back s_setprio 0/1 pair in the middle of every 32-MFMA segment (16 sites)
# speedup vs baseline: 1.0114x; 1.0102x over previous
.Lpeel_join375_1:
	s_waitcnt lgkmcnt(0)
	s_barrier
	s_setprio 1
	s_waitcnt lgkmcnt(0)
	v_mfma_f32_16x16x32_bf16 v[120:123], v[128:131], v[178:181], 0
	v_mfma_f32_16x16x32_bf16 v[124:127], v[136:139], v[178:181], 0
	v_mfma_f32_16x16x32_bf16 v[100:103], v[128:131], v[206:209], 0
	v_mfma_f32_16x16x32_bf16 v[96:99], v[136:139], v[206:209], 0
	v_mfma_f32_16x16x32_bf16 v[84:87], v[128:131], v[214:217], 0
	v_mfma_f32_16x16x32_bf16 v[80:83], v[136:139], v[214:217], 0
	v_mfma_f32_16x16x32_bf16 v[68:71], v[128:131], v[222:225], 0
	v_mfma_f32_16x16x32_bf16 v[64:67], v[136:139], v[222:225], 0
	v_mfma_f32_16x16x32_bf16 v[120:123], v[132:135], v[202:205], v[120:123]
	v_mfma_f32_16x16x32_bf16 v[124:127], v[140:143], v[202:205], v[124:127]
	v_mfma_f32_16x16x32_bf16 v[100:103], v[132:135], v[210:213], v[100:103]
	v_mfma_f32_16x16x32_bf16 v[96:99], v[140:143], v[210:213], v[96:99]
	v_mfma_f32_16x16x32_bf16 v[84:87], v[132:135], v[218:221], v[84:87]
	v_mfma_f32_16x16x32_bf16 v[80:83], v[140:143], v[218:221], v[80:83]
	v_mfma_f32_16x16x32_bf16 v[68:71], v[132:135], v[226:229], v[68:71]
	v_mfma_f32_16x16x32_bf16 v[64:67], v[140:143], v[226:229], v[64:67]
	v_mfma_f32_16x16x32_bf16 v[116:119], v[144:147], v[178:181], 0
	v_mfma_f32_16x16x32_bf16 v[112:115], v[170:173], v[178:181], 0
	v_mfma_f32_16x16x32_bf16 v[108:111], v[144:147], v[206:209], 0
	v_mfma_f32_16x16x32_bf16 v[104:107], v[170:173], v[206:209], 0
	v_mfma_f32_16x16x32_bf16 v[92:95], v[144:147], v[214:217], 0
	v_mfma_f32_16x16x32_bf16 v[88:91], v[170:173], v[214:217], 0
	v_mfma_f32_16x16x32_bf16 v[76:79], v[144:147], v[222:225], 0
	v_mfma_f32_16x16x32_bf16 v[72:75], v[170:173], v[222:225], 0
	v_mfma_f32_16x16x32_bf16 v[116:119], v[148:151], v[202:205], v[116:119]
	v_mfma_f32_16x16x32_bf16 v[112:115], v[174:177], v[202:205], v[112:115]
	v_mfma_f32_16x16x32_bf16 v[108:111], v[148:151], v[210:213], v[108:111]
	v_mfma_f32_16x16x32_bf16 v[104:107], v[174:177], v[210:213], v[104:107]
	v_mfma_f32_16x16x32_bf16 v[92:95], v[148:151], v[218:221], v[92:95]
	v_mfma_f32_16x16x32_bf16 v[88:91], v[174:177], v[218:221], v[88:91]
	v_mfma_f32_16x16x32_bf16 v[76:79], v[148:151], v[226:229], v[76:79]
	v_mfma_f32_16x16x32_bf16 v[72:75], v[174:177], v[226:229], v[72:75]
	s_setprio 0
	s_barrier
	s_add_i32 s12, s12, s17
	v_lshl_add_u64 v[230:231], s[14:15], 0, v[154:155]
	s_mov_b32 m0, s12
	ds_read_b128 v[178:181], v157 offset:16384
	ds_read_b128 v[202:205], v157 offset:17408
	ds_read_b128 v[206:209], v157 offset:18432
	ds_read_b128 v[210:213], v157 offset:19456
	ds_read_b128 v[214:217], v157 offset:20480
	ds_read_b128 v[218:221], v157 offset:21504
	ds_read_b128 v[222:225], v157 offset:22528
	ds_read_b128 v[226:229], v157 offset:23552
	global_load_lds_dwordx4 v[230:231], off
	s_add_i32 m0, s12, 0x2000
	v_lshl_add_u64 v[232:233], s[14:15], 0, v[162:163]
	s_add_u32 s14, s14, s24
	s_addc_u32 s15, s15, s25
	s_add_i32 s2, s2, s17
	global_load_lds_dwordx4 v[232:233], off
	v_lshl_add_u64 v[234:235], s[14:15], 0, v[154:155]
	s_mov_b32 m0, s2
	v_lshl_add_u64 v[236:237], s[14:15], 0, v[162:163]
	global_load_lds_dwordx4 v[234:235], off
	s_add_i32 m0, s2, 0x2000
	v_lshl_add_u64 v[238:239], s[0:1], 0, v[158:159]
	global_load_lds_dwordx4 v[236:237], off
	s_mov_b32 m0, s45
	v_lshl_add_u64 v[240:241], s[0:1], 0, v[160:161]
	global_load_lds_dwordx4 v[238:239], off
	s_mov_b32 m0, s83
	s_nop 0
	global_load_lds_dwordx4 v[240:241], off
	s_lshl_b32 s99, s17, 1
	s_add_i32 m0, s99, 0x20000
	s_lshl_b32 s98, s65, 14
	s_add_i32 s98, s98, s99
	s_add_u32 s98, s100, s98
	s_addc_u32 s99, s101, 0
	global_load_lds_dwordx4 v248, s[98:99]
	global_load_lds_dwordx4 v248, s[98:99] offset:1024
	s_cmp_eq_u32 s18, 1
	s_cbranch_scc1 .Lpeel_strict375_2
	s_waitcnt vmcnt(18)
	s_branch .Lpeel_join375_2

.Lpeel_join375_2:
	s_waitcnt lgkmcnt(0)
	s_barrier
	s_setprio 1
	s_waitcnt lgkmcnt(0)
	v_mfma_f32_16x16x32_bf16 v[52:55], v[128:131], v[178:181], 0
	v_mfma_f32_16x16x32_bf16 v[48:51], v[136:139], v[178:181], 0
	v_mfma_f32_16x16x32_bf16 v[36:39], v[128:131], v[206:209], 0
	v_mfma_f32_16x16x32_bf16 v[32:35], v[136:139], v[206:209], 0
	v_mfma_f32_16x16x32_bf16 v[20:23], v[128:131], v[214:217], 0
	v_mfma_f32_16x16x32_bf16 v[16:19], v[136:139], v[214:217], 0
	v_mfma_f32_16x16x32_bf16 v[4:7], v[128:131], v[222:225], 0
	v_mfma_f32_16x16x32_bf16 v[0:3], v[136:139], v[222:225], 0
	v_mfma_f32_16x16x32_bf16 v[52:55], v[132:135], v[202:205], v[52:55]
	v_mfma_f32_16x16x32_bf16 v[48:51], v[140:143], v[202:205], v[48:51]
	v_mfma_f32_16x16x32_bf16 v[36:39], v[132:135], v[210:213], v[36:39]
	v_mfma_f32_16x16x32_bf16 v[32:35], v[140:143], v[210:213], v[32:35]
	v_mfma_f32_16x16x32_bf16 v[20:23], v[132:135], v[218:221], v[20:23]
	v_mfma_f32_16x16x32_bf16 v[16:19], v[140:143], v[218:221], v[16:19]
	v_mfma_f32_16x16x32_bf16 v[4:7], v[132:135], v[226:229], v[4:7]
	v_mfma_f32_16x16x32_bf16 v[0:3], v[140:143], v[226:229], v[0:3]
	v_mfma_f32_16x16x32_bf16 v[60:63], v[144:147], v[178:181], 0
	v_mfma_f32_16x16x32_bf16 v[56:59], v[170:173], v[178:181], 0
	v_mfma_f32_16x16x32_bf16 v[44:47], v[144:147], v[206:209], 0
	v_mfma_f32_16x16x32_bf16 v[40:43], v[170:173], v[206:209], 0
	v_mfma_f32_16x16x32_bf16 v[28:31], v[144:147], v[214:217], 0
	v_mfma_f32_16x16x32_bf16 v[24:27], v[170:173], v[214:217], 0
	v_mfma_f32_16x16x32_bf16 v[12:15], v[144:147], v[222:225], 0
	v_mfma_f32_16x16x32_bf16 v[8:11], v[170:173], v[222:225], 0
	v_mfma_f32_16x16x32_bf16 v[60:63], v[148:151], v[202:205], v[60:63]
	v_mfma_f32_16x16x32_bf16 v[56:59], v[174:177], v[202:205], v[56:59]
	v_mfma_f32_16x16x32_bf16 v[44:47], v[148:151], v[210:213], v[44:47]
	v_mfma_f32_16x16x32_bf16 v[40:43], v[174:177], v[210:213], v[40:43]
	v_mfma_f32_16x16x32_bf16 v[28:31], v[148:151], v[218:221], v[28:31]
	v_mfma_f32_16x16x32_bf16 v[24:27], v[174:177], v[218:221], v[24:27]
	v_mfma_f32_16x16x32_bf16 v[12:15], v[148:151], v[226:229], v[12:15]
	v_mfma_f32_16x16x32_bf16 v[8:11], v[174:177], v[226:229], v[8:11]
	s_setprio 0
	s_barrier
	s_add_i32 s2, 0, 0x18000
	s_add_i32 s12, 0, 0x1c000
	v_add_u32_e32 v140, s2, v195
	v_add_u32_e32 v174, s12, v195
	ds_read_b128 v[128:131], v140
	ds_read_b128 v[132:135], v140 offset:1024
	ds_read_b128 v[136:139], v140 offset:2048
	ds_read_b128 v[140:143], v140 offset:3072
	ds_read_b128 v[144:147], v174
	ds_read_b128 v[148:151], v174 offset:1024
	ds_read_b128 v[170:173], v174 offset:2048
	ds_read_b128 v[174:177], v174 offset:3072
	s_add_u32 s0, s0, s8
	s_addc_u32 s1, s1, s9
	s_mov_b32 m0, s28
	v_lshl_add_u64 v[242:243], s[0:1], 0, v[158:159]
	ds_read_b128 v[178:181], v157 offset:32768
	ds_read_b128 v[202:205], v157 offset:33792
	ds_read_b128 v[206:209], v157 offset:34816
	ds_read_b128 v[210:213], v157 offset:35840
	ds_read_b128 v[214:217], v157 offset:36864
	ds_read_b128 v[218:221], v157 offset:37888
	ds_read_b128 v[222:225], v157 offset:38912
	ds_read_b128 v[226:229], v157 offset:39936
	global_load_lds_dwordx4 v[242:243], off
	v_lshl_add_u64 v[242:243], s[0:1], 0, v[160:161]
	s_mov_b32 m0, s29
	s_nop 0
	global_load_lds_dwordx4 v[242:243], off
	s_waitcnt vmcnt(10)
	s_waitcnt lgkmcnt(0)
	s_barrier
	s_setprio 1
	s_waitcnt lgkmcnt(0)
	v_mfma_f32_16x16x32_bf16 v[120:123], v[128:131], v[178:181], v[120:123]
	v_mfma_f32_16x16x32_bf16 v[124:127], v[136:139], v[178:181], v[124:127]
	v_mfma_f32_16x16x32_bf16 v[100:103], v[128:131], v[206:209], v[100:103]
	v_mfma_f32_16x16x32_bf16 v[96:99], v[136:139], v[206:209], v[96:99]
	v_mfma_f32_16x16x32_bf16 v[84:87], v[128:131], v[214:217], v[84:87]
	v_mfma_f32_16x16x32_bf16 v[80:83], v[136:139], v[214:217], v[80:83]
	v_mfma_f32_16x16x32_bf16 v[68:71], v[128:131], v[222:225], v[68:71]
	v_mfma_f32_16x16x32_bf16 v[64:67], v[136:139], v[222:225], v[64:67]
	v_mfma_f32_16x16x32_bf16 v[120:123], v[132:135], v[202:205], v[120:123]
	v_mfma_f32_16x16x32_bf16 v[124:127], v[140:143], v[202:205], v[124:127]
	v_mfma_f32_16x16x32_bf16 v[100:103], v[132:135], v[210:213], v[100:103]
	v_mfma_f32_16x16x32_bf16 v[96:99], v[140:143], v[210:213], v[96:99]
	v_mfma_f32_16x16x32_bf16 v[84:87], v[132:135], v[218:221], v[84:87]
	v_mfma_f32_16x16x32_bf16 v[80:83], v[140:143], v[218:221], v[80:83]
	v_mfma_f32_16x16x32_bf16 v[68:71], v[132:135], v[226:229], v[68:71]
	v_mfma_f32_16x16x32_bf16 v[64:67], v[140:143], v[226:229], v[64:67]
	v_mfma_f32_16x16x32_bf16 v[116:119], v[144:147], v[178:181], v[116:119]
	v_mfma_f32_16x16x32_bf16 v[112:115], v[170:173], v[178:181], v[112:115]
	v_mfma_f32_16x16x32_bf16 v[108:111], v[144:147], v[206:209], v[108:111]
	v_mfma_f32_16x16x32_bf16 v[104:107], v[170:173], v[206:209], v[104:107]
	v_mfma_f32_16x16x32_bf16 v[92:95], v[144:147], v[214:217], v[92:95]
	v_mfma_f32_16x16x32_bf16 v[88:91], v[170:173], v[214:217], v[88:91]
	v_mfma_f32_16x16x32_bf16 v[76:79], v[144:147], v[222:225], v[76:79]
	v_mfma_f32_16x16x32_bf16 v[72:75], v[170:173], v[222:225], v[72:75]
	v_mfma_f32_16x16x32_bf16 v[116:119], v[148:151], v[202:205], v[116:119]
	v_mfma_f32_16x16x32_bf16 v[112:115], v[174:177], v[202:205], v[112:115]
	v_mfma_f32_16x16x32_bf16 v[108:111], v[148:151], v[210:213], v[108:111]
	v_mfma_f32_16x16x32_bf16 v[104:107], v[174:177], v[210:213], v[104:107]
	v_mfma_f32_16x16x32_bf16 v[92:95], v[148:151], v[218:221], v[92:95]
	v_mfma_f32_16x16x32_bf16 v[88:91], v[174:177], v[218:221], v[88:91]
	v_mfma_f32_16x16x32_bf16 v[76:79], v[148:151], v[226:229], v[76:79]
	v_mfma_f32_16x16x32_bf16 v[72:75], v[174:177], v[226:229], v[72:75]
	s_setprio 0
	s_barrier
	s_add_i32 s0, s2, s17
	v_lshl_add_u64 v[230:231], v[230:231], 0, s[36:37]
	s_mov_b32 m0, s0
	ds_read_b128 v[178:181], v157 offset:49152
	ds_read_b128 v[202:205], v157 offset:50176
	ds_read_b128 v[206:209], v157 offset:51200
	ds_read_b128 v[210:213], v157 offset:52224
	ds_read_b128 v[214:217], v157 offset:53248
	ds_read_b128 v[218:221], v157 offset:54272
	ds_read_b128 v[222:225], v157 offset:55296
	ds_read_b128 v[226:229], v157 offset:56320
	global_load_lds_dwordx4 v[230:231], off
	v_lshl_add_u64 v[230:231], v[232:233], 0, s[36:37]
	s_add_i32 m0, s0, 0x2000
	s_add_i32 s0, s12, s17
	global_load_lds_dwordx4 v[230:231], off
	v_lshl_add_u64 v[230:231], v[234:235], 0, s[36:37]
	s_mov_b32 m0, s0
	s_nop 0
	global_load_lds_dwordx4 v[230:231], off
	v_lshl_add_u64 v[230:231], v[236:237], 0, s[36:37]
	s_add_i32 m0, s0, 0x2000
	s_nop 0
	global_load_lds_dwordx4 v[230:231], off
	v_lshl_add_u64 v[230:231], v[238:239], 0, s[36:37]
	s_mov_b32 m0, s10
	s_nop 0
	global_load_lds_dwordx4 v[230:231], off
	v_lshl_add_u64 v[230:231], v[240:241], 0, s[36:37]
	s_mov_b32 m0, s11
	s_nop 0
	global_load_lds_dwordx4 v[230:231], off
	s_waitcnt vmcnt(10)
	s_waitcnt lgkmcnt(0)
	s_barrier
	s_setprio 1
	s_waitcnt lgkmcnt(0)
	v_mfma_f32_16x16x32_bf16 v[52:55], v[128:131], v[178:181], v[52:55]
	v_mfma_f32_16x16x32_bf16 v[48:51], v[136:139], v[178:181], v[48:51]
	v_mfma_f32_16x16x32_bf16 v[36:39], v[128:131], v[206:209], v[36:39]
	v_mfma_f32_16x16x32_bf16 v[32:35], v[136:139], v[206:209], v[32:35]
	v_mfma_f32_16x16x32_bf16 v[20:23], v[128:131], v[214:217], v[20:23]
	v_mfma_f32_16x16x32_bf16 v[16:19], v[136:139], v[214:217], v[16:19]
	v_mfma_f32_16x16x32_bf16 v[4:7], v[128:131], v[222:225], v[4:7]
	v_mfma_f32_16x16x32_bf16 v[0:3], v[136:139], v[222:225], v[0:3]
	v_mfma_f32_16x16x32_bf16 v[52:55], v[132:135], v[202:205], v[52:55]
	v_mfma_f32_16x16x32_bf16 v[48:51], v[140:143], v[202:205], v[48:51]
	v_mfma_f32_16x16x32_bf16 v[36:39], v[132:135], v[210:213], v[36:39]
	v_mfma_f32_16x16x32_bf16 v[32:35], v[140:143], v[210:213], v[32:35]
	v_mfma_f32_16x16x32_bf16 v[20:23], v[132:135], v[218:221], v[20:23]
	v_mfma_f32_16x16x32_bf16 v[16:19], v[140:143], v[218:221], v[16:19]
	v_mfma_f32_16x16x32_bf16 v[4:7], v[132:135], v[226:229], v[4:7]
	v_mfma_f32_16x16x32_bf16 v[0:3], v[140:143], v[226:229], v[0:3]
	v_mfma_f32_16x16x32_bf16 v[60:63], v[144:147], v[178:181], v[60:63]
	v_mfma_f32_16x16x32_bf16 v[56:59], v[170:173], v[178:181], v[56:59]
	v_mfma_f32_16x16x32_bf16 v[44:47], v[144:147], v[206:209], v[44:47]
	v_mfma_f32_16x16x32_bf16 v[40:43], v[170:173], v[206:209], v[40:43]
	v_mfma_f32_16x16x32_bf16 v[28:31], v[144:147], v[214:217], v[28:31]
	v_mfma_f32_16x16x32_bf16 v[24:27], v[170:173], v[214:217], v[24:27]
	v_mfma_f32_16x16x32_bf16 v[12:15], v[144:147], v[222:225], v[12:15]
	v_mfma_f32_16x16x32_bf16 v[8:11], v[170:173], v[222:225], v[8:11]
	v_mfma_f32_16x16x32_bf16 v[60:63], v[148:151], v[202:205], v[60:63]
	v_mfma_f32_16x16x32_bf16 v[56:59], v[174:177], v[202:205], v[56:59]
	v_mfma_f32_16x16x32_bf16 v[44:47], v[148:151], v[210:213], v[44:47]
	v_mfma_f32_16x16x32_bf16 v[40:43], v[174:177], v[210:213], v[40:43]
	v_mfma_f32_16x16x32_bf16 v[28:31], v[148:151], v[218:221], v[28:31]
	v_mfma_f32_16x16x32_bf16 v[24:27], v[174:177], v[218:221], v[24:27]
	v_mfma_f32_16x16x32_bf16 v[12:15], v[148:151], v[226:229], v[12:15]
	v_mfma_f32_16x16x32_bf16 v[8:11], v[174:177], v[226:229], v[8:11]
	s_setprio 0
	s_barrier
	s_add_u32 s42, s42, 0x100
	s_addc_u32 s43, s43, 0
	s_add_u32 s46, s46, 0x100
	s_addc_u32 s47, s47, 0
	s_cmp_ge_u32 s97, s31
	s_mov_b32 s0, s97
.LBB0_375:
	s_add_i32 s97, s0, 2
	s_add_u32 s2, s42, 0x80
	s_addc_u32 s1, s43, 0
	s_add_i32 s12, 0, 0x10000
	s_cmp_eq_u32 s13, s0
	s_cselect_b32 s1, s95, s1
	s_cselect_b32 s0, s94, s2
	s_cselect_b32 s15, s55, s47
	s_cselect_b32 s14, s54, s46
	s_add_i32 s2, 0, 0x14000
	v_add_u32_e32 v140, s12, v195
	v_add_u32_e32 v174, s2, v195
	ds_read_b128 v[128:131], v140
	ds_read_b128 v[132:135], v140 offset:1024
	ds_read_b128 v[136:139], v140 offset:2048
	ds_read_b128 v[140:143], v140 offset:3072
	ds_read_b128 v[144:147], v174
	ds_read_b128 v[148:151], v174 offset:1024
	ds_read_b128 v[170:173], v174 offset:2048
	ds_read_b128 v[174:177], v174 offset:3072
	v_lshl_add_u64 v[230:231], s[42:43], 0, v[166:167]
	s_add_i32 m0, s45, 0xc000
	ds_read_b128 v[178:181], v157
	ds_read_b128 v[202:205], v157 offset:1024
	ds_read_b128 v[206:209], v157 offset:2048
	ds_read_b128 v[210:213], v157 offset:3072
	ds_read_b128 v[214:217], v157 offset:4096
	ds_read_b128 v[218:221], v157 offset:5120
	ds_read_b128 v[222:225], v157 offset:6144
	ds_read_b128 v[226:229], v157 offset:7168
	global_load_lds_dwordx4 v[230:231], off
	v_lshl_add_u64 v[230:231], s[42:43], 0, v[168:169]
	s_add_i32 m0, s45, 0xe000
	s_nop 0
	global_load_lds_dwordx4 v[230:231], off
	s_waitcnt vmcnt(8)
	s_waitcnt lgkmcnt(0)
	s_barrier
	s_setprio 1
	s_waitcnt lgkmcnt(0)
	v_mfma_f32_16x16x32_bf16 v[120:123], v[128:131], v[178:181], v[120:123]
	v_mfma_f32_16x16x32_bf16 v[124:127], v[136:139], v[178:181], v[124:127]
	v_mfma_f32_16x16x32_bf16 v[100:103], v[128:131], v[206:209], v[100:103]
	v_mfma_f32_16x16x32_bf16 v[96:99], v[136:139], v[206:209], v[96:99]
	v_mfma_f32_16x16x32_bf16 v[84:87], v[128:131], v[214:217], v[84:87]
	v_mfma_f32_16x16x32_bf16 v[80:83], v[136:139], v[214:217], v[80:83]
	v_mfma_f32_16x16x32_bf16 v[68:71], v[128:131], v[222:225], v[68:71]
	v_mfma_f32_16x16x32_bf16 v[64:67], v[136:139], v[222:225], v[64:67]
	v_mfma_f32_16x16x32_bf16 v[120:123], v[132:135], v[202:205], v[120:123]
	v_mfma_f32_16x16x32_bf16 v[124:127], v[140:143], v[202:205], v[124:127]
	v_mfma_f32_16x16x32_bf16 v[100:103], v[132:135], v[210:213], v[100:103]
	v_mfma_f32_16x16x32_bf16 v[96:99], v[140:143], v[210:213], v[96:99]
	v_mfma_f32_16x16x32_bf16 v[84:87], v[132:135], v[218:221], v[84:87]
	v_mfma_f32_16x16x32_bf16 v[80:83], v[140:143], v[218:221], v[80:83]
	v_mfma_f32_16x16x32_bf16 v[68:71], v[132:135], v[226:229], v[68:71]
	v_mfma_f32_16x16x32_bf16 v[64:67], v[140:143], v[226:229], v[64:67]
	v_mfma_f32_16x16x32_bf16 v[116:119], v[144:147], v[178:181], v[116:119]
	v_mfma_f32_16x16x32_bf16 v[112:115], v[170:173], v[178:181], v[112:115]
	v_mfma_f32_16x16x32_bf16 v[108:111], v[144:147], v[206:209], v[108:111]
	v_mfma_f32_16x16x32_bf16 v[104:107], v[170:173], v[206:209], v[104:107]
	v_mfma_f32_16x16x32_bf16 v[92:95], v[144:147], v[214:217], v[92:95]
	v_mfma_f32_16x16x32_bf16 v[88:91], v[170:173], v[214:217], v[88:91]
	v_mfma_f32_16x16x32_bf16 v[76:79], v[144:147], v[222:225], v[76:79]
	v_mfma_f32_16x16x32_bf16 v[72:75], v[170:173], v[222:225], v[72:75]
	v_mfma_f32_16x16x32_bf16 v[116:119], v[148:151], v[202:205], v[116:119]
	v_mfma_f32_16x16x32_bf16 v[112:115], v[174:177], v[202:205], v[112:115]
	v_mfma_f32_16x16x32_bf16 v[108:111], v[148:151], v[210:213], v[108:111]
	v_mfma_f32_16x16x32_bf16 v[104:107], v[174:177], v[210:213], v[104:107]
	v_mfma_f32_16x16x32_bf16 v[92:95], v[148:151], v[218:221], v[92:95]
	v_mfma_f32_16x16x32_bf16 v[88:91], v[174:177], v[218:221], v[88:91]
	v_mfma_f32_16x16x32_bf16 v[76:79], v[148:151], v[226:229], v[76:79]
	v_mfma_f32_16x16x32_bf16 v[72:75], v[174:177], v[226:229], v[72:75]
	s_setprio 0
	s_barrier
	s_add_i32 s12, s12, s17
	v_lshl_add_u64 v[230:231], s[14:15], 0, v[154:155]
	s_mov_b32 m0, s12
	ds_read_b128 v[178:181], v157 offset:16384
	ds_read_b128 v[202:205], v157 offset:17408
	ds_read_b128 v[206:209], v157 offset:18432
	ds_read_b128 v[210:213], v157 offset:19456
	ds_read_b128 v[214:217], v157 offset:20480
	ds_read_b128 v[218:221], v157 offset:21504
	ds_read_b128 v[222:225], v157 offset:22528
	ds_read_b128 v[226:229], v157 offset:23552
	global_load_lds_dwordx4 v[230:231], off
	s_add_i32 m0, s12, 0x2000
	v_lshl_add_u64 v[232:233], s[14:15], 0, v[162:163]
	s_add_u32 s14, s14, s24
	s_addc_u32 s15, s15, s25
	s_add_i32 s2, s2, s17
	global_load_lds_dwordx4 v[232:233], off
	v_lshl_add_u64 v[234:235], s[14:15], 0, v[154:155]
	s_mov_b32 m0, s2
	v_lshl_add_u64 v[236:237], s[14:15], 0, v[162:163]
	global_load_lds_dwordx4 v[234:235], off
	s_add_i32 m0, s2, 0x2000
	v_lshl_add_u64 v[238:239], s[0:1], 0, v[158:159]
	global_load_lds_dwordx4 v[236:237], off
	s_mov_b32 m0, s45
	v_lshl_add_u64 v[240:241], s[0:1], 0, v[160:161]
	global_load_lds_dwordx4 v[238:239], off
	s_mov_b32 m0, s83
	s_nop 0
	global_load_lds_dwordx4 v[240:241], off
	s_waitcnt vmcnt(8)
	s_waitcnt lgkmcnt(0)
	s_barrier
	s_setprio 1
	s_waitcnt lgkmcnt(0)
	v_mfma_f32_16x16x32_bf16 v[52:55], v[128:131], v[178:181], v[52:55]
	v_mfma_f32_16x16x32_bf16 v[48:51], v[136:139], v[178:181], v[48:51]
	v_mfma_f32_16x16x32_bf16 v[36:39], v[128:131], v[206:209], v[36:39]
	v_mfma_f32_16x16x32_bf16 v[32:35], v[136:139], v[206:209], v[32:35]
	v_mfma_f32_16x16x32_bf16 v[20:23], v[128:131], v[214:217], v[20:23]
	v_mfma_f32_16x16x32_bf16 v[16:19], v[136:139], v[214:217], v[16:19]
	v_mfma_f32_16x16x32_bf16 v[4:7], v[128:131], v[222:225], v[4:7]
	v_mfma_f32_16x16x32_bf16 v[0:3], v[136:139], v[222:225], v[0:3]
	v_mfma_f32_16x16x32_bf16 v[52:55], v[132:135], v[202:205], v[52:55]
	v_mfma_f32_16x16x32_bf16 v[48:51], v[140:143], v[202:205], v[48:51]
	v_mfma_f32_16x16x32_bf16 v[36:39], v[132:135], v[210:213], v[36:39]
	v_mfma_f32_16x16x32_bf16 v[32:35], v[140:143], v[210:213], v[32:35]
	v_mfma_f32_16x16x32_bf16 v[20:23], v[132:135], v[218:221], v[20:23]
	v_mfma_f32_16x16x32_bf16 v[16:19], v[140:143], v[218:221], v[16:19]
	v_mfma_f32_16x16x32_bf16 v[4:7], v[132:135], v[226:229], v[4:7]
	v_mfma_f32_16x16x32_bf16 v[0:3], v[140:143], v[226:229], v[0:3]
	v_mfma_f32_16x16x32_bf16 v[60:63], v[144:147], v[178:181], v[60:63]
	v_mfma_f32_16x16x32_bf16 v[56:59], v[170:173], v[178:181], v[56:59]
	v_mfma_f32_16x16x32_bf16 v[44:47], v[144:147], v[206:209], v[44:47]
	v_mfma_f32_16x16x32_bf16 v[40:43], v[170:173], v[206:209], v[40:43]
	v_mfma_f32_16x16x32_bf16 v[28:31], v[144:147], v[214:217], v[28:31]
	v_mfma_f32_16x16x32_bf16 v[24:27], v[170:173], v[214:217], v[24:27]
	v_mfma_f32_16x16x32_bf16 v[12:15], v[144:147], v[222:225], v[12:15]
	v_mfma_f32_16x16x32_bf16 v[8:11], v[170:173], v[222:225], v[8:11]
	v_mfma_f32_16x16x32_bf16 v[60:63], v[148:151], v[202:205], v[60:63]
	v_mfma_f32_16x16x32_bf16 v[56:59], v[174:177], v[202:205], v[56:59]
	v_mfma_f32_16x16x32_bf16 v[44:47], v[148:151], v[210:213], v[44:47]
	v_mfma_f32_16x16x32_bf16 v[40:43], v[174:177], v[210:213], v[40:43]
	v_mfma_f32_16x16x32_bf16 v[28:31], v[148:151], v[218:221], v[28:31]
	v_mfma_f32_16x16x32_bf16 v[24:27], v[174:177], v[218:221], v[24:27]
	v_mfma_f32_16x16x32_bf16 v[12:15], v[148:151], v[226:229], v[12:15]
	v_mfma_f32_16x16x32_bf16 v[8:11], v[174:177], v[226:229], v[8:11]
	s_setprio 0
	s_barrier
	s_add_i32 s2, 0, 0x18000
	s_add_i32 s12, 0, 0x1c000
	v_add_u32_e32 v140, s2, v195
	v_add_u32_e32 v174, s12, v195
	ds_read_b128 v[128:131], v140
	ds_read_b128 v[132:135], v140 offset:1024
	ds_read_b128 v[136:139], v140 offset:2048
	ds_read_b128 v[140:143], v140 offset:3072
	ds_read_b128 v[144:147], v174
	ds_read_b128 v[148:151], v174 offset:1024
	ds_read_b128 v[170:173], v174 offset:2048
	ds_read_b128 v[174:177], v174 offset:3072
	s_add_u32 s0, s0, s8
	s_addc_u32 s1, s1, s9
	s_mov_b32 m0, s28
	v_lshl_add_u64 v[242:243], s[0:1], 0, v[158:159]
	ds_read_b128 v[178:181], v157 offset:32768
	ds_read_b128 v[202:205], v157 offset:33792
	ds_read_b128 v[206:209], v157 offset:34816
	ds_read_b128 v[210:213], v157 offset:35840
	ds_read_b128 v[214:217], v157 offset:36864
	ds_read_b128 v[218:221], v157 offset:37888
	ds_read_b128 v[222:225], v157 offset:38912
	ds_read_b128 v[226:229], v157 offset:39936
	global_load_lds_dwordx4 v[242:243], off
	v_lshl_add_u64 v[242:243], s[0:1], 0, v[160:161]
	s_mov_b32 m0, s29
	s_nop 0
	global_load_lds_dwordx4 v[242:243], off
	s_waitcnt vmcnt(8)
	s_waitcnt lgkmcnt(0)
	s_barrier
	s_setprio 1
	s_waitcnt lgkmcnt(0)
	v_mfma_f32_16x16x32_bf16 v[120:123], v[128:131], v[178:181], v[120:123]
	v_mfma_f32_16x16x32_bf16 v[124:127], v[136:139], v[178:181], v[124:127]
	v_mfma_f32_16x16x32_bf16 v[100:103], v[128:131], v[206:209], v[100:103]
	v_mfma_f32_16x16x32_bf16 v[96:99], v[136:139], v[206:209], v[96:99]
	v_mfma_f32_16x16x32_bf16 v[84:87], v[128:131], v[214:217], v[84:87]
	v_mfma_f32_16x16x32_bf16 v[80:83], v[136:139], v[214:217], v[80:83]
	v_mfma_f32_16x16x32_bf16 v[68:71], v[128:131], v[222:225], v[68:71]
	v_mfma_f32_16x16x32_bf16 v[64:67], v[136:139], v[222:225], v[64:67]
	v_mfma_f32_16x16x32_bf16 v[120:123], v[132:135], v[202:205], v[120:123]
	v_mfma_f32_16x16x32_bf16 v[124:127], v[140:143], v[202:205], v[124:127]
	v_mfma_f32_16x16x32_bf16 v[100:103], v[132:135], v[210:213], v[100:103]
	v_mfma_f32_16x16x32_bf16 v[96:99], v[140:143], v[210:213], v[96:99]
	v_mfma_f32_16x16x32_bf16 v[84:87], v[132:135], v[218:221], v[84:87]
	v_mfma_f32_16x16x32_bf16 v[80:83], v[140:143], v[218:221], v[80:83]
	v_mfma_f32_16x16x32_bf16 v[68:71], v[132:135], v[226:229], v[68:71]
	v_mfma_f32_16x16x32_bf16 v[64:67], v[140:143], v[226:229], v[64:67]
	v_mfma_f32_16x16x32_bf16 v[116:119], v[144:147], v[178:181], v[116:119]
	v_mfma_f32_16x16x32_bf16 v[112:115], v[170:173], v[178:181], v[112:115]
	v_mfma_f32_16x16x32_bf16 v[108:111], v[144:147], v[206:209], v[108:111]
	v_mfma_f32_16x16x32_bf16 v[104:107], v[170:173], v[206:209], v[104:107]
	v_mfma_f32_16x16x32_bf16 v[92:95], v[144:147], v[214:217], v[92:95]
	v_mfma_f32_16x16x32_bf16 v[88:91], v[170:173], v[214:217], v[88:91]
	v_mfma_f32_16x16x32_bf16 v[76:79], v[144:147], v[222:225], v[76:79]
	v_mfma_f32_16x16x32_bf16 v[72:75], v[170:173], v[222:225], v[72:75]
	v_mfma_f32_16x16x32_bf16 v[116:119], v[148:151], v[202:205], v[116:119]
	v_mfma_f32_16x16x32_bf16 v[112:115], v[174:177], v[202:205], v[112:115]
	v_mfma_f32_16x16x32_bf16 v[108:111], v[148:151], v[210:213], v[108:111]
	v_mfma_f32_16x16x32_bf16 v[104:107], v[174:177], v[210:213], v[104:107]
	v_mfma_f32_16x16x32_bf16 v[92:95], v[148:151], v[218:221], v[92:95]
	v_mfma_f32_16x16x32_bf16 v[88:91], v[174:177], v[218:221], v[88:91]
	v_mfma_f32_16x16x32_bf16 v[76:79], v[148:151], v[226:229], v[76:79]
	v_mfma_f32_16x16x32_bf16 v[72:75], v[174:177], v[226:229], v[72:75]
	s_setprio 0
	s_barrier
	s_add_i32 s0, s2, s17
	v_lshl_add_u64 v[230:231], v[230:231], 0, s[36:37]
	s_mov_b32 m0, s0
	ds_read_b128 v[178:181], v157 offset:49152
	ds_read_b128 v[202:205], v157 offset:50176
	ds_read_b128 v[206:209], v157 offset:51200
	ds_read_b128 v[210:213], v157 offset:52224
	ds_read_b128 v[214:217], v157 offset:53248
	ds_read_b128 v[218:221], v157 offset:54272
	ds_read_b128 v[222:225], v157 offset:55296
	ds_read_b128 v[226:229], v157 offset:56320
	global_load_lds_dwordx4 v[230:231], off
	v_lshl_add_u64 v[230:231], v[232:233], 0, s[36:37]
	s_add_i32 m0, s0, 0x2000
	s_add_i32 s0, s12, s17
	global_load_lds_dwordx4 v[230:231], off
	v_lshl_add_u64 v[230:231], v[234:235], 0, s[36:37]
	s_mov_b32 m0, s0
	s_nop 0
	global_load_lds_dwordx4 v[230:231], off
	v_lshl_add_u64 v[230:231], v[236:237], 0, s[36:37]
	s_add_i32 m0, s0, 0x2000
	s_nop 0
	global_load_lds_dwordx4 v[230:231], off
	v_lshl_add_u64 v[230:231], v[238:239], 0, s[36:37]
	s_mov_b32 m0, s10
	s_nop 0
	global_load_lds_dwordx4 v[230:231], off
	v_lshl_add_u64 v[230:231], v[240:241], 0, s[36:37]
	s_mov_b32 m0, s11
	s_nop 0
	global_load_lds_dwordx4 v[230:231], off
	s_waitcnt vmcnt(8)
	s_waitcnt lgkmcnt(0)
	s_barrier
	s_setprio 1
	s_waitcnt lgkmcnt(0)
	v_mfma_f32_16x16x32_bf16 v[52:55], v[128:131], v[178:181], v[52:55]
	v_mfma_f32_16x16x32_bf16 v[48:51], v[136:139], v[178:181], v[48:51]
	v_mfma_f32_16x16x32_bf16 v[36:39], v[128:131], v[206:209], v[36:39]
	v_mfma_f32_16x16x32_bf16 v[32:35], v[136:139], v[206:209], v[32:35]
	v_mfma_f32_16x16x32_bf16 v[20:23], v[128:131], v[214:217], v[20:23]
	v_mfma_f32_16x16x32_bf16 v[16:19], v[136:139], v[214:217], v[16:19]
	v_mfma_f32_16x16x32_bf16 v[4:7], v[128:131], v[222:225], v[4:7]
	v_mfma_f32_16x16x32_bf16 v[0:3], v[136:139], v[222:225], v[0:3]
	v_mfma_f32_16x16x32_bf16 v[52:55], v[132:135], v[202:205], v[52:55]
	v_mfma_f32_16x16x32_bf16 v[48:51], v[140:143], v[202:205], v[48:51]
	v_mfma_f32_16x16x32_bf16 v[36:39], v[132:135], v[210:213], v[36:39]
	v_mfma_f32_16x16x32_bf16 v[32:35], v[140:143], v[210:213], v[32:35]
	v_mfma_f32_16x16x32_bf16 v[20:23], v[132:135], v[218:221], v[20:23]
	v_mfma_f32_16x16x32_bf16 v[16:19], v[140:143], v[218:221], v[16:19]
	v_mfma_f32_16x16x32_bf16 v[4:7], v[132:135], v[226:229], v[4:7]
	v_mfma_f32_16x16x32_bf16 v[0:3], v[140:143], v[226:229], v[0:3]
	v_mfma_f32_16x16x32_bf16 v[60:63], v[144:147], v[178:181], v[60:63]
	v_mfma_f32_16x16x32_bf16 v[56:59], v[170:173], v[178:181], v[56:59]
	v_mfma_f32_16x16x32_bf16 v[44:47], v[144:147], v[206:209], v[44:47]
	v_mfma_f32_16x16x32_bf16 v[40:43], v[170:173], v[206:209], v[40:43]
	v_mfma_f32_16x16x32_bf16 v[28:31], v[144:147], v[214:217], v[28:31]
	v_mfma_f32_16x16x32_bf16 v[24:27], v[170:173], v[214:217], v[24:27]
	v_mfma_f32_16x16x32_bf16 v[12:15], v[144:147], v[222:225], v[12:15]
	v_mfma_f32_16x16x32_bf16 v[8:11], v[170:173], v[222:225], v[8:11]
	v_mfma_f32_16x16x32_bf16 v[60:63], v[148:151], v[202:205], v[60:63]
	v_mfma_f32_16x16x32_bf16 v[56:59], v[174:177], v[202:205], v[56:59]
	v_mfma_f32_16x16x32_bf16 v[44:47], v[148:151], v[210:213], v[44:47]
	v_mfma_f32_16x16x32_bf16 v[40:43], v[174:177], v[210:213], v[40:43]
	v_mfma_f32_16x16x32_bf16 v[28:31], v[148:151], v[218:221], v[28:31]
	v_mfma_f32_16x16x32_bf16 v[24:27], v[174:177], v[218:221], v[24:27]
	v_mfma_f32_16x16x32_bf16 v[12:15], v[148:151], v[226:229], v[12:15]
	v_mfma_f32_16x16x32_bf16 v[8:11], v[174:177], v[226:229], v[8:11]
	s_setprio 0
	s_barrier
	s_add_u32 s42, s42, 0x100
	s_addc_u32 s43, s43, 0
	s_add_u32 s46, s46, 0x100
	s_addc_u32 s47, s47, 0
	s_cmp_ge_u32 s97, s31
	s_mov_b32 s0, s97
	s_cbranch_scc0 .LBB0_375
	s_and_b64 vcc, exec, s[74:75]
	s_cbranch_vccz .LBB0_378
	s_barrier

.Lpeel_join482_1:
	s_waitcnt lgkmcnt(0)
	s_barrier
	s_setprio 1
	s_waitcnt lgkmcnt(0)
	v_mfma_f32_16x16x32_bf16 v[124:127], v[128:131], v[202:205], 0
	v_mfma_f32_16x16x32_bf16 v[120:123], v[146:149], v[202:205], 0
	v_mfma_f32_16x16x32_bf16 v[108:111], v[128:131], v[210:213], 0
	v_mfma_f32_16x16x32_bf16 v[104:107], v[146:149], v[210:213], 0
	v_mfma_f32_16x16x32_bf16 v[92:95], v[128:131], v[218:221], 0
	v_mfma_f32_16x16x32_bf16 v[88:91], v[146:149], v[218:221], 0
	v_mfma_f32_16x16x32_bf16 v[76:79], v[128:131], v[226:229], 0
	v_mfma_f32_16x16x32_bf16 v[72:75], v[146:149], v[226:229], 0
	v_mfma_f32_16x16x32_bf16 v[124:127], v[132:135], v[206:209], v[124:127]
	v_mfma_f32_16x16x32_bf16 v[120:123], v[158:161], v[206:209], v[120:123]
	v_mfma_f32_16x16x32_bf16 v[108:111], v[132:135], v[214:217], v[108:111]
	v_mfma_f32_16x16x32_bf16 v[104:107], v[158:161], v[214:217], v[104:107]
	v_mfma_f32_16x16x32_bf16 v[92:95], v[132:135], v[222:225], v[92:95]
	v_mfma_f32_16x16x32_bf16 v[88:91], v[158:161], v[222:225], v[88:91]
	v_mfma_f32_16x16x32_bf16 v[76:79], v[132:135], v[230:233], v[76:79]
	v_mfma_f32_16x16x32_bf16 v[72:75], v[158:161], v[230:233], v[72:75]
	v_mfma_f32_16x16x32_bf16 v[116:119], v[168:171], v[202:205], 0
	v_mfma_f32_16x16x32_bf16 v[112:115], v[176:179], v[202:205], 0
	v_mfma_f32_16x16x32_bf16 v[100:103], v[168:171], v[210:213], 0
	v_mfma_f32_16x16x32_bf16 v[96:99], v[176:179], v[210:213], 0
	v_mfma_f32_16x16x32_bf16 v[84:87], v[168:171], v[218:221], 0
	v_mfma_f32_16x16x32_bf16 v[80:83], v[176:179], v[218:221], 0
	v_mfma_f32_16x16x32_bf16 v[68:71], v[168:171], v[226:229], 0
	v_mfma_f32_16x16x32_bf16 v[64:67], v[176:179], v[226:229], 0
	v_mfma_f32_16x16x32_bf16 v[116:119], v[172:175], v[206:209], v[116:119]
	v_mfma_f32_16x16x32_bf16 v[112:115], v[194:197], v[206:209], v[112:115]
	v_mfma_f32_16x16x32_bf16 v[100:103], v[172:175], v[214:217], v[100:103]
	v_mfma_f32_16x16x32_bf16 v[96:99], v[194:197], v[214:217], v[96:99]
	v_mfma_f32_16x16x32_bf16 v[84:87], v[172:175], v[222:225], v[84:87]
	v_mfma_f32_16x16x32_bf16 v[80:83], v[194:197], v[222:225], v[80:83]
	v_mfma_f32_16x16x32_bf16 v[68:71], v[172:175], v[230:233], v[68:71]
	v_mfma_f32_16x16x32_bf16 v[64:67], v[194:197], v[230:233], v[64:67]
	s_setprio 0
	s_barrier
	s_add_i32 s15, s15, s2
	v_lshl_add_u64 v[150:151], s[82:83], 0, v[154:155]
	s_mov_b32 m0, s15
	ds_read_b128 v[202:205], v167 offset:16384
	ds_read_b128 v[206:209], v167 offset:17408
	ds_read_b128 v[210:213], v167 offset:18432
	ds_read_b128 v[214:217], v167 offset:19456
	ds_read_b128 v[218:221], v167 offset:20480
	ds_read_b128 v[222:225], v167 offset:21504
	ds_read_b128 v[226:229], v167 offset:22528
	ds_read_b128 v[230:233], v167 offset:23552
	global_load_lds_dwordx4 v[150:151], off
	s_add_i32 m0, s15, 0x2000
	v_lshl_add_u64 v[162:163], s[82:83], 0, v[140:141]
	s_add_u32 s82, s82, s24
	s_addc_u32 s83, s83, s25
	s_add_i32 s14, s14, s2
	global_load_lds_dwordx4 v[162:163], off
	v_lshl_add_u64 v[180:181], s[82:83], 0, v[154:155]
	s_mov_b32 m0, s14
	v_lshl_add_u64 v[234:235], s[82:83], 0, v[140:141]
	global_load_lds_dwordx4 v[180:181], off
	s_add_i32 m0, s14, 0x2000
	v_lshl_add_u64 v[236:237], s[0:1], 0, v[136:137]
	global_load_lds_dwordx4 v[234:235], off
	s_mov_b32 m0, s3
	v_lshl_add_u64 v[238:239], s[0:1], 0, v[138:139]
	global_load_lds_dwordx4 v[236:237], off
	s_mov_b32 m0, s10
	s_nop 0
	global_load_lds_dwordx4 v[238:239], off
	s_cmp_eq_u32 s92, 1
	s_cbranch_scc1 .Lpeel_strict482_2
	s_waitcnt vmcnt(24)
	s_branch .Lpeel_join482_2

.Lpeel_join482_2:
	s_waitcnt lgkmcnt(0)
	s_barrier
	s_setprio 1
	s_waitcnt lgkmcnt(0)
	v_mfma_f32_16x16x32_bf16 v[60:63], v[128:131], v[202:205], 0
	v_mfma_f32_16x16x32_bf16 v[56:59], v[146:149], v[202:205], 0
	v_mfma_f32_16x16x32_bf16 v[44:47], v[128:131], v[210:213], 0
	v_mfma_f32_16x16x32_bf16 v[40:43], v[146:149], v[210:213], 0
	v_mfma_f32_16x16x32_bf16 v[28:31], v[128:131], v[218:221], 0
	v_mfma_f32_16x16x32_bf16 v[24:27], v[146:149], v[218:221], 0
	v_mfma_f32_16x16x32_bf16 v[12:15], v[128:131], v[226:229], 0
	v_mfma_f32_16x16x32_bf16 v[8:11], v[146:149], v[226:229], 0
	v_mfma_f32_16x16x32_bf16 v[60:63], v[132:135], v[206:209], v[60:63]
	v_mfma_f32_16x16x32_bf16 v[56:59], v[158:161], v[206:209], v[56:59]
	v_mfma_f32_16x16x32_bf16 v[44:47], v[132:135], v[214:217], v[44:47]
	v_mfma_f32_16x16x32_bf16 v[40:43], v[158:161], v[214:217], v[40:43]
	v_mfma_f32_16x16x32_bf16 v[28:31], v[132:135], v[222:225], v[28:31]
	v_mfma_f32_16x16x32_bf16 v[24:27], v[158:161], v[222:225], v[24:27]
	v_mfma_f32_16x16x32_bf16 v[12:15], v[132:135], v[230:233], v[12:15]
	v_mfma_f32_16x16x32_bf16 v[8:11], v[158:161], v[230:233], v[8:11]
	v_mfma_f32_16x16x32_bf16 v[52:55], v[168:171], v[202:205], 0
	v_mfma_f32_16x16x32_bf16 v[48:51], v[176:179], v[202:205], 0
	v_mfma_f32_16x16x32_bf16 v[36:39], v[168:171], v[210:213], 0
	v_mfma_f32_16x16x32_bf16 v[32:35], v[176:179], v[210:213], 0
	v_mfma_f32_16x16x32_bf16 v[20:23], v[168:171], v[218:221], 0
	v_mfma_f32_16x16x32_bf16 v[16:19], v[176:179], v[218:221], 0
	v_mfma_f32_16x16x32_bf16 v[4:7], v[168:171], v[226:229], 0
	v_mfma_f32_16x16x32_bf16 v[0:3], v[176:179], v[226:229], 0
	v_mfma_f32_16x16x32_bf16 v[52:55], v[172:175], v[206:209], v[52:55]
	v_mfma_f32_16x16x32_bf16 v[48:51], v[194:197], v[206:209], v[48:51]
	v_mfma_f32_16x16x32_bf16 v[36:39], v[172:175], v[214:217], v[36:39]
	v_mfma_f32_16x16x32_bf16 v[32:35], v[194:197], v[214:217], v[32:35]
	v_mfma_f32_16x16x32_bf16 v[20:23], v[172:175], v[222:225], v[20:23]
	v_mfma_f32_16x16x32_bf16 v[16:19], v[194:197], v[222:225], v[16:19]
	v_mfma_f32_16x16x32_bf16 v[4:7], v[172:175], v[230:233], v[4:7]
	v_mfma_f32_16x16x32_bf16 v[0:3], v[194:197], v[230:233], v[0:3]
	s_setprio 0
	s_barrier
	s_add_i32 s14, 0, 0x18000
	s_add_i32 s15, 0, 0x1c000
	v_add_u32_e32 v158, s14, v165
	v_add_u32_e32 v193, s15, v165
	ds_read_b128 v[128:131], v158
	ds_read_b128 v[132:135], v158 offset:1024
	ds_read_b128 v[146:149], v158 offset:2048
	ds_read_b128 v[158:161], v158 offset:3072
	ds_read_b128 v[168:171], v193
	ds_read_b128 v[172:175], v193 offset:1024
	ds_read_b128 v[176:179], v193 offset:2048
	ds_read_b128 v[194:197], v193 offset:3072
	s_add_u32 s0, s0, s8
	s_addc_u32 s1, s1, s9
	s_mov_b32 m0, s11
	v_lshl_add_u64 v[240:241], s[0:1], 0, v[136:137]
	ds_read_b128 v[202:205], v167 offset:32768
	ds_read_b128 v[206:209], v167 offset:33792
	ds_read_b128 v[210:213], v167 offset:34816
	ds_read_b128 v[214:217], v167 offset:35840
	ds_read_b128 v[218:221], v167 offset:36864
	ds_read_b128 v[222:225], v167 offset:37888
	ds_read_b128 v[226:229], v167 offset:38912
	ds_read_b128 v[230:233], v167 offset:39936
	global_load_lds_dwordx4 v[240:241], off
	v_lshl_add_u64 v[240:241], s[0:1], 0, v[138:139]
	s_mov_b32 m0, s13
	s_nop 0
	global_load_lds_dwordx4 v[240:241], off
	s_waitcnt vmcnt(8)
	s_waitcnt lgkmcnt(0)
	s_barrier
	s_setprio 1
	s_waitcnt lgkmcnt(0)
	v_mfma_f32_16x16x32_bf16 v[124:127], v[128:131], v[202:205], v[124:127]
	v_mfma_f32_16x16x32_bf16 v[120:123], v[146:149], v[202:205], v[120:123]
	v_mfma_f32_16x16x32_bf16 v[108:111], v[128:131], v[210:213], v[108:111]
	v_mfma_f32_16x16x32_bf16 v[104:107], v[146:149], v[210:213], v[104:107]
	v_mfma_f32_16x16x32_bf16 v[92:95], v[128:131], v[218:221], v[92:95]
	v_mfma_f32_16x16x32_bf16 v[88:91], v[146:149], v[218:221], v[88:91]
	v_mfma_f32_16x16x32_bf16 v[76:79], v[128:131], v[226:229], v[76:79]
	v_mfma_f32_16x16x32_bf16 v[72:75], v[146:149], v[226:229], v[72:75]
	v_mfma_f32_16x16x32_bf16 v[124:127], v[132:135], v[206:209], v[124:127]
	v_mfma_f32_16x16x32_bf16 v[120:123], v[158:161], v[206:209], v[120:123]
	v_mfma_f32_16x16x32_bf16 v[108:111], v[132:135], v[214:217], v[108:111]
	v_mfma_f32_16x16x32_bf16 v[104:107], v[158:161], v[214:217], v[104:107]
	v_mfma_f32_16x16x32_bf16 v[92:95], v[132:135], v[222:225], v[92:95]
	v_mfma_f32_16x16x32_bf16 v[88:91], v[158:161], v[222:225], v[88:91]
	v_mfma_f32_16x16x32_bf16 v[76:79], v[132:135], v[230:233], v[76:79]
	v_mfma_f32_16x16x32_bf16 v[72:75], v[158:161], v[230:233], v[72:75]
	v_mfma_f32_16x16x32_bf16 v[116:119], v[168:171], v[202:205], v[116:119]
	v_mfma_f32_16x16x32_bf16 v[112:115], v[176:179], v[202:205], v[112:115]
	v_mfma_f32_16x16x32_bf16 v[100:103], v[168:171], v[210:213], v[100:103]
	v_mfma_f32_16x16x32_bf16 v[96:99], v[176:179], v[210:213], v[96:99]
	v_mfma_f32_16x16x32_bf16 v[84:87], v[168:171], v[218:221], v[84:87]
	v_mfma_f32_16x16x32_bf16 v[80:83], v[176:179], v[218:221], v[80:83]
	v_mfma_f32_16x16x32_bf16 v[68:71], v[168:171], v[226:229], v[68:71]
	v_mfma_f32_16x16x32_bf16 v[64:67], v[176:179], v[226:229], v[64:67]
	v_mfma_f32_16x16x32_bf16 v[116:119], v[172:175], v[206:209], v[116:119]
	v_mfma_f32_16x16x32_bf16 v[112:115], v[194:197], v[206:209], v[112:115]
	v_mfma_f32_16x16x32_bf16 v[100:103], v[172:175], v[214:217], v[100:103]
	v_mfma_f32_16x16x32_bf16 v[96:99], v[194:197], v[214:217], v[96:99]
	v_mfma_f32_16x16x32_bf16 v[84:87], v[172:175], v[222:225], v[84:87]
	v_mfma_f32_16x16x32_bf16 v[80:83], v[194:197], v[222:225], v[80:83]
	v_mfma_f32_16x16x32_bf16 v[68:71], v[172:175], v[230:233], v[68:71]
	v_mfma_f32_16x16x32_bf16 v[64:67], v[194:197], v[230:233], v[64:67]
	s_setprio 0
	s_barrier
	s_add_i32 s0, s14, s2
	v_lshl_add_u64 v[150:151], v[150:151], 0, s[36:37]
	s_mov_b32 m0, s0
	ds_read_b128 v[202:205], v167 offset:49152
	ds_read_b128 v[206:209], v167 offset:50176
	ds_read_b128 v[210:213], v167 offset:51200
	ds_read_b128 v[214:217], v167 offset:52224
	ds_read_b128 v[218:221], v167 offset:53248
	ds_read_b128 v[222:225], v167 offset:54272
	ds_read_b128 v[226:229], v167 offset:55296
	ds_read_b128 v[230:233], v167 offset:56320
	global_load_lds_dwordx4 v[150:151], off
	v_lshl_add_u64 v[150:151], v[162:163], 0, s[36:37]
	s_add_i32 m0, s0, 0x2000
	s_add_i32 s0, s15, s2
	global_load_lds_dwordx4 v[150:151], off
	v_lshl_add_u64 v[150:151], v[180:181], 0, s[36:37]
	s_mov_b32 m0, s0
	s_nop 0
	global_load_lds_dwordx4 v[150:151], off
	v_lshl_add_u64 v[150:151], v[234:235], 0, s[36:37]
	s_add_i32 m0, s0, 0x2000
	s_nop 0
	global_load_lds_dwordx4 v[150:151], off
	v_lshl_add_u64 v[150:151], v[236:237], 0, s[36:37]
	s_mov_b32 m0, s18
	s_nop 0
	global_load_lds_dwordx4 v[150:151], off
	v_lshl_add_u64 v[150:151], v[238:239], 0, s[36:37]
	s_mov_b32 m0, s28
	s_nop 0
	global_load_lds_dwordx4 v[150:151], off
	s_waitcnt vmcnt(8)
	s_waitcnt lgkmcnt(0)
	s_barrier
	s_setprio 1
	s_waitcnt lgkmcnt(0)
	v_mfma_f32_16x16x32_bf16 v[60:63], v[128:131], v[202:205], v[60:63]
	v_mfma_f32_16x16x32_bf16 v[56:59], v[146:149], v[202:205], v[56:59]
	v_mfma_f32_16x16x32_bf16 v[44:47], v[128:131], v[210:213], v[44:47]
	v_mfma_f32_16x16x32_bf16 v[40:43], v[146:149], v[210:213], v[40:43]
	v_mfma_f32_16x16x32_bf16 v[28:31], v[128:131], v[218:221], v[28:31]
	v_mfma_f32_16x16x32_bf16 v[24:27], v[146:149], v[218:221], v[24:27]
	v_mfma_f32_16x16x32_bf16 v[12:15], v[128:131], v[226:229], v[12:15]
	v_mfma_f32_16x16x32_bf16 v[8:11], v[146:149], v[226:229], v[8:11]
	v_mfma_f32_16x16x32_bf16 v[60:63], v[132:135], v[206:209], v[60:63]
	v_mfma_f32_16x16x32_bf16 v[56:59], v[158:161], v[206:209], v[56:59]
	v_mfma_f32_16x16x32_bf16 v[44:47], v[132:135], v[214:217], v[44:47]
	v_mfma_f32_16x16x32_bf16 v[40:43], v[158:161], v[214:217], v[40:43]
	v_mfma_f32_16x16x32_bf16 v[28:31], v[132:135], v[222:225], v[28:31]
	v_mfma_f32_16x16x32_bf16 v[24:27], v[158:161], v[222:225], v[24:27]
	v_mfma_f32_16x16x32_bf16 v[12:15], v[132:135], v[230:233], v[12:15]
	v_mfma_f32_16x16x32_bf16 v[8:11], v[158:161], v[230:233], v[8:11]
	v_mfma_f32_16x16x32_bf16 v[52:55], v[168:171], v[202:205], v[52:55]
	v_mfma_f32_16x16x32_bf16 v[48:51], v[176:179], v[202:205], v[48:51]
	v_mfma_f32_16x16x32_bf16 v[36:39], v[168:171], v[210:213], v[36:39]
	v_mfma_f32_16x16x32_bf16 v[32:35], v[176:179], v[210:213], v[32:35]
	v_mfma_f32_16x16x32_bf16 v[20:23], v[168:171], v[218:221], v[20:23]
	v_mfma_f32_16x16x32_bf16 v[16:19], v[176:179], v[218:221], v[16:19]
	v_mfma_f32_16x16x32_bf16 v[4:7], v[168:171], v[226:229], v[4:7]
	v_mfma_f32_16x16x32_bf16 v[0:3], v[176:179], v[226:229], v[0:3]
	v_mfma_f32_16x16x32_bf16 v[52:55], v[172:175], v[206:209], v[52:55]
	v_mfma_f32_16x16x32_bf16 v[48:51], v[194:197], v[206:209], v[48:51]
	v_mfma_f32_16x16x32_bf16 v[36:39], v[172:175], v[214:217], v[36:39]
	v_mfma_f32_16x16x32_bf16 v[32:35], v[194:197], v[214:217], v[32:35]
	v_mfma_f32_16x16x32_bf16 v[20:23], v[172:175], v[222:225], v[20:23]
	v_mfma_f32_16x16x32_bf16 v[16:19], v[194:197], v[222:225], v[16:19]
	v_mfma_f32_16x16x32_bf16 v[4:7], v[172:175], v[230:233], v[4:7]
	v_mfma_f32_16x16x32_bf16 v[0:3], v[194:197], v[230:233], v[0:3]
	s_setprio 0
	s_barrier
	s_add_u32 s42, s42, 0x100
	s_addc_u32 s43, s43, 0
	s_add_u32 s44, s44, 0x100
	s_addc_u32 s45, s45, 0
	s_cmp_ge_u32 s47, s31
	s_mov_b32 s0, s47
.LBB0_482:
	s_add_i32 s47, s0, 2
	s_add_u32 s14, s42, 0x80
	s_addc_u32 s1, s43, 0
	s_add_i32 s15, 0, 0x10000
	s_cmp_eq_u32 s29, s0
	s_cselect_b32 s1, s77, s1
	s_cselect_b32 s0, s76, s14
	v_add_u32_e32 v150, s15, v165
	s_cselect_b32 s83, s79, s45
	s_cselect_b32 s82, s78, s44
	s_add_i32 s14, 0, 0x14000
	ds_read_b128 v[128:131], v150
	ds_read_b128 v[132:135], v150 offset:1024
	ds_read_b128 v[146:149], v150 offset:2048
	ds_read_b128 v[158:161], v150 offset:3072
	v_add_u32_e32 v150, s14, v165
	ds_read_b128 v[168:171], v150
	ds_read_b128 v[172:175], v150 offset:1024
	ds_read_b128 v[176:179], v150 offset:2048
	ds_read_b128 v[194:197], v150 offset:3072
	v_lshl_add_u64 v[150:151], s[42:43], 0, v[142:143]
	s_add_i32 m0, s3, 0xc000
	ds_read_b128 v[202:205], v167
	ds_read_b128 v[206:209], v167 offset:1024
	ds_read_b128 v[210:213], v167 offset:2048
	ds_read_b128 v[214:217], v167 offset:3072
	ds_read_b128 v[218:221], v167 offset:4096
	ds_read_b128 v[222:225], v167 offset:5120
	ds_read_b128 v[226:229], v167 offset:6144
	ds_read_b128 v[230:233], v167 offset:7168
	global_load_lds_dwordx4 v[150:151], off
	v_lshl_add_u64 v[150:151], s[42:43], 0, v[144:145]
	s_add_i32 m0, s3, 0xe000
	s_nop 0
	global_load_lds_dwordx4 v[150:151], off
	s_waitcnt vmcnt(8)
	s_waitcnt lgkmcnt(0)
	s_barrier
	s_setprio 1
	s_waitcnt lgkmcnt(0)
	v_mfma_f32_16x16x32_bf16 v[124:127], v[128:131], v[202:205], v[124:127]
	v_mfma_f32_16x16x32_bf16 v[120:123], v[146:149], v[202:205], v[120:123]
	v_mfma_f32_16x16x32_bf16 v[108:111], v[128:131], v[210:213], v[108:111]
	v_mfma_f32_16x16x32_bf16 v[104:107], v[146:149], v[210:213], v[104:107]
	v_mfma_f32_16x16x32_bf16 v[92:95], v[128:131], v[218:221], v[92:95]
	v_mfma_f32_16x16x32_bf16 v[88:91], v[146:149], v[218:221], v[88:91]
	v_mfma_f32_16x16x32_bf16 v[76:79], v[128:131], v[226:229], v[76:79]
	v_mfma_f32_16x16x32_bf16 v[72:75], v[146:149], v[226:229], v[72:75]
	v_mfma_f32_16x16x32_bf16 v[124:127], v[132:135], v[206:209], v[124:127]
	v_mfma_f32_16x16x32_bf16 v[120:123], v[158:161], v[206:209], v[120:123]
	v_mfma_f32_16x16x32_bf16 v[108:111], v[132:135], v[214:217], v[108:111]
	v_mfma_f32_16x16x32_bf16 v[104:107], v[158:161], v[214:217], v[104:107]
	v_mfma_f32_16x16x32_bf16 v[92:95], v[132:135], v[222:225], v[92:95]
	v_mfma_f32_16x16x32_bf16 v[88:91], v[158:161], v[222:225], v[88:91]
	v_mfma_f32_16x16x32_bf16 v[76:79], v[132:135], v[230:233], v[76:79]
	v_mfma_f32_16x16x32_bf16 v[72:75], v[158:161], v[230:233], v[72:75]
	v_mfma_f32_16x16x32_bf16 v[116:119], v[168:171], v[202:205], v[116:119]
	v_mfma_f32_16x16x32_bf16 v[112:115], v[176:179], v[202:205], v[112:115]
	v_mfma_f32_16x16x32_bf16 v[100:103], v[168:171], v[210:213], v[100:103]
	v_mfma_f32_16x16x32_bf16 v[96:99], v[176:179], v[210:213], v[96:99]
	v_mfma_f32_16x16x32_bf16 v[84:87], v[168:171], v[218:221], v[84:87]
	v_mfma_f32_16x16x32_bf16 v[80:83], v[176:179], v[218:221], v[80:83]
	v_mfma_f32_16x16x32_bf16 v[68:71], v[168:171], v[226:229], v[68:71]
	v_mfma_f32_16x16x32_bf16 v[64:67], v[176:179], v[226:229], v[64:67]
	v_mfma_f32_16x16x32_bf16 v[116:119], v[172:175], v[206:209], v[116:119]
	v_mfma_f32_16x16x32_bf16 v[112:115], v[194:197], v[206:209], v[112:115]
	v_mfma_f32_16x16x32_bf16 v[100:103], v[172:175], v[214:217], v[100:103]
	v_mfma_f32_16x16x32_bf16 v[96:99], v[194:197], v[214:217], v[96:99]
	v_mfma_f32_16x16x32_bf16 v[84:87], v[172:175], v[222:225], v[84:87]
	v_mfma_f32_16x16x32_bf16 v[80:83], v[194:197], v[222:225], v[80:83]
	v_mfma_f32_16x16x32_bf16 v[68:71], v[172:175], v[230:233], v[68:71]
	v_mfma_f32_16x16x32_bf16 v[64:67], v[194:197], v[230:233], v[64:67]
	s_setprio 0
	s_barrier
	s_add_i32 s15, s15, s2
	v_lshl_add_u64 v[150:151], s[82:83], 0, v[154:155]
	s_mov_b32 m0, s15
	ds_read_b128 v[202:205], v167 offset:16384
	ds_read_b128 v[206:209], v167 offset:17408
	ds_read_b128 v[210:213], v167 offset:18432
	ds_read_b128 v[214:217], v167 offset:19456
	ds_read_b128 v[218:221], v167 offset:20480
	ds_read_b128 v[222:225], v167 offset:21504
	ds_read_b128 v[226:229], v167 offset:22528
	ds_read_b128 v[230:233], v167 offset:23552
	global_load_lds_dwordx4 v[150:151], off
	s_add_i32 m0, s15, 0x2000
	v_lshl_add_u64 v[162:163], s[82:83], 0, v[140:141]
	s_add_u32 s82, s82, s24
	s_addc_u32 s83, s83, s25
	s_add_i32 s14, s14, s2
	global_load_lds_dwordx4 v[162:163], off
	v_lshl_add_u64 v[180:181], s[82:83], 0, v[154:155]
	s_mov_b32 m0, s14
	v_lshl_add_u64 v[234:235], s[82:83], 0, v[140:141]
	global_load_lds_dwordx4 v[180:181], off
	s_add_i32 m0, s14, 0x2000
	v_lshl_add_u64 v[236:237], s[0:1], 0, v[136:137]
	global_load_lds_dwordx4 v[234:235], off
	s_mov_b32 m0, s3
	v_lshl_add_u64 v[238:239], s[0:1], 0, v[138:139]
	global_load_lds_dwordx4 v[236:237], off
	s_mov_b32 m0, s10
	s_nop 0
	global_load_lds_dwordx4 v[238:239], off
	s_waitcnt vmcnt(8)
	s_waitcnt lgkmcnt(0)
	s_barrier
	s_setprio 1
	s_waitcnt lgkmcnt(0)
	v_mfma_f32_16x16x32_bf16 v[60:63], v[128:131], v[202:205], v[60:63]
	v_mfma_f32_16x16x32_bf16 v[56:59], v[146:149], v[202:205], v[56:59]
	v_mfma_f32_16x16x32_bf16 v[44:47], v[128:131], v[210:213], v[44:47]
	v_mfma_f32_16x16x32_bf16 v[40:43], v[146:149], v[210:213], v[40:43]
	v_mfma_f32_16x16x32_bf16 v[28:31], v[128:131], v[218:221], v[28:31]
	v_mfma_f32_16x16x32_bf16 v[24:27], v[146:149], v[218:221], v[24:27]
	v_mfma_f32_16x16x32_bf16 v[12:15], v[128:131], v[226:229], v[12:15]
	v_mfma_f32_16x16x32_bf16 v[8:11], v[146:149], v[226:229], v[8:11]
	v_mfma_f32_16x16x32_bf16 v[60:63], v[132:135], v[206:209], v[60:63]
	v_mfma_f32_16x16x32_bf16 v[56:59], v[158:161], v[206:209], v[56:59]
	v_mfma_f32_16x16x32_bf16 v[44:47], v[132:135], v[214:217], v[44:47]
	v_mfma_f32_16x16x32_bf16 v[40:43], v[158:161], v[214:217], v[40:43]
	v_mfma_f32_16x16x32_bf16 v[28:31], v[132:135], v[222:225], v[28:31]
	v_mfma_f32_16x16x32_bf16 v[24:27], v[158:161], v[222:225], v[24:27]
	v_mfma_f32_16x16x32_bf16 v[12:15], v[132:135], v[230:233], v[12:15]
	v_mfma_f32_16x16x32_bf16 v[8:11], v[158:161], v[230:233], v[8:11]
	v_mfma_f32_16x16x32_bf16 v[52:55], v[168:171], v[202:205], v[52:55]
	v_mfma_f32_16x16x32_bf16 v[48:51], v[176:179], v[202:205], v[48:51]
	v_mfma_f32_16x16x32_bf16 v[36:39], v[168:171], v[210:213], v[36:39]
	v_mfma_f32_16x16x32_bf16 v[32:35], v[176:179], v[210:213], v[32:35]
	v_mfma_f32_16x16x32_bf16 v[20:23], v[168:171], v[218:221], v[20:23]
	v_mfma_f32_16x16x32_bf16 v[16:19], v[176:179], v[218:221], v[16:19]
	v_mfma_f32_16x16x32_bf16 v[4:7], v[168:171], v[226:229], v[4:7]
	v_mfma_f32_16x16x32_bf16 v[0:3], v[176:179], v[226:229], v[0:3]
	v_mfma_f32_16x16x32_bf16 v[52:55], v[172:175], v[206:209], v[52:55]
	v_mfma_f32_16x16x32_bf16 v[48:51], v[194:197], v[206:209], v[48:51]
	v_mfma_f32_16x16x32_bf16 v[36:39], v[172:175], v[214:217], v[36:39]
	v_mfma_f32_16x16x32_bf16 v[32:35], v[194:197], v[214:217], v[32:35]
	v_mfma_f32_16x16x32_bf16 v[20:23], v[172:175], v[222:225], v[20:23]
	v_mfma_f32_16x16x32_bf16 v[16:19], v[194:197], v[222:225], v[16:19]
	v_mfma_f32_16x16x32_bf16 v[4:7], v[172:175], v[230:233], v[4:7]
	v_mfma_f32_16x16x32_bf16 v[0:3], v[194:197], v[230:233], v[0:3]
	s_setprio 0
	s_barrier
	s_add_i32 s14, 0, 0x18000
	s_add_i32 s15, 0, 0x1c000
	v_add_u32_e32 v158, s14, v165
	v_add_u32_e32 v193, s15, v165
	ds_read_b128 v[128:131], v158
	ds_read_b128 v[132:135], v158 offset:1024
	ds_read_b128 v[146:149], v158 offset:2048
	ds_read_b128 v[158:161], v158 offset:3072
	ds_read_b128 v[168:171], v193
	ds_read_b128 v[172:175], v193 offset:1024
	ds_read_b128 v[176:179], v193 offset:2048
	ds_read_b128 v[194:197], v193 offset:3072
	s_add_u32 s0, s0, s8
	s_addc_u32 s1, s1, s9
	s_mov_b32 m0, s11
	v_lshl_add_u64 v[240:241], s[0:1], 0, v[136:137]
	ds_read_b128 v[202:205], v167 offset:32768
	ds_read_b128 v[206:209], v167 offset:33792
	ds_read_b128 v[210:213], v167 offset:34816
	ds_read_b128 v[214:217], v167 offset:35840
	ds_read_b128 v[218:221], v167 offset:36864
	ds_read_b128 v[222:225], v167 offset:37888
	ds_read_b128 v[226:229], v167 offset:38912
	ds_read_b128 v[230:233], v167 offset:39936
	global_load_lds_dwordx4 v[240:241], off
	v_lshl_add_u64 v[240:241], s[0:1], 0, v[138:139]
	s_mov_b32 m0, s13
	s_nop 0
	global_load_lds_dwordx4 v[240:241], off
	s_waitcnt vmcnt(8)
	s_waitcnt lgkmcnt(0)
	s_barrier
	s_setprio 1
	s_waitcnt lgkmcnt(0)
	v_mfma_f32_16x16x32_bf16 v[124:127], v[128:131], v[202:205], v[124:127]
	v_mfma_f32_16x16x32_bf16 v[120:123], v[146:149], v[202:205], v[120:123]
	v_mfma_f32_16x16x32_bf16 v[108:111], v[128:131], v[210:213], v[108:111]
	v_mfma_f32_16x16x32_bf16 v[104:107], v[146:149], v[210:213], v[104:107]
	v_mfma_f32_16x16x32_bf16 v[92:95], v[128:131], v[218:221], v[92:95]
	v_mfma_f32_16x16x32_bf16 v[88:91], v[146:149], v[218:221], v[88:91]
	v_mfma_f32_16x16x32_bf16 v[76:79], v[128:131], v[226:229], v[76:79]
	v_mfma_f32_16x16x32_bf16 v[72:75], v[146:149], v[226:229], v[72:75]
	v_mfma_f32_16x16x32_bf16 v[124:127], v[132:135], v[206:209], v[124:127]
	v_mfma_f32_16x16x32_bf16 v[120:123], v[158:161], v[206:209], v[120:123]
	v_mfma_f32_16x16x32_bf16 v[108:111], v[132:135], v[214:217], v[108:111]
	v_mfma_f32_16x16x32_bf16 v[104:107], v[158:161], v[214:217], v[104:107]
	v_mfma_f32_16x16x32_bf16 v[92:95], v[132:135], v[222:225], v[92:95]
	v_mfma_f32_16x16x32_bf16 v[88:91], v[158:161], v[222:225], v[88:91]
	v_mfma_f32_16x16x32_bf16 v[76:79], v[132:135], v[230:233], v[76:79]
	v_mfma_f32_16x16x32_bf16 v[72:75], v[158:161], v[230:233], v[72:75]
	v_mfma_f32_16x16x32_bf16 v[116:119], v[168:171], v[202:205], v[116:119]
	v_mfma_f32_16x16x32_bf16 v[112:115], v[176:179], v[202:205], v[112:115]
	v_mfma_f32_16x16x32_bf16 v[100:103], v[168:171], v[210:213], v[100:103]
	v_mfma_f32_16x16x32_bf16 v[96:99], v[176:179], v[210:213], v[96:99]
	v_mfma_f32_16x16x32_bf16 v[84:87], v[168:171], v[218:221], v[84:87]
	v_mfma_f32_16x16x32_bf16 v[80:83], v[176:179], v[218:221], v[80:83]
	v_mfma_f32_16x16x32_bf16 v[68:71], v[168:171], v[226:229], v[68:71]
	v_mfma_f32_16x16x32_bf16 v[64:67], v[176:179], v[226:229], v[64:67]
	v_mfma_f32_16x16x32_bf16 v[116:119], v[172:175], v[206:209], v[116:119]
	v_mfma_f32_16x16x32_bf16 v[112:115], v[194:197], v[206:209], v[112:115]
	v_mfma_f32_16x16x32_bf16 v[100:103], v[172:175], v[214:217], v[100:103]
	v_mfma_f32_16x16x32_bf16 v[96:99], v[194:197], v[214:217], v[96:99]
	v_mfma_f32_16x16x32_bf16 v[84:87], v[172:175], v[222:225], v[84:87]
	v_mfma_f32_16x16x32_bf16 v[80:83], v[194:197], v[222:225], v[80:83]
	v_mfma_f32_16x16x32_bf16 v[68:71], v[172:175], v[230:233], v[68:71]
	v_mfma_f32_16x16x32_bf16 v[64:67], v[194:197], v[230:233], v[64:67]
	s_setprio 0
	s_barrier
	s_add_i32 s0, s14, s2
	v_lshl_add_u64 v[150:151], v[150:151], 0, s[36:37]
	s_mov_b32 m0, s0
	ds_read_b128 v[202:205], v167 offset:49152
	ds_read_b128 v[206:209], v167 offset:50176
	ds_read_b128 v[210:213], v167 offset:51200
	ds_read_b128 v[214:217], v167 offset:52224
	ds_read_b128 v[218:221], v167 offset:53248
	ds_read_b128 v[222:225], v167 offset:54272
	ds_read_b128 v[226:229], v167 offset:55296
	ds_read_b128 v[230:233], v167 offset:56320
	global_load_lds_dwordx4 v[150:151], off
	v_lshl_add_u64 v[150:151], v[162:163], 0, s[36:37]
	s_add_i32 m0, s0, 0x2000
	s_add_i32 s0, s15, s2
	global_load_lds_dwordx4 v[150:151], off
	v_lshl_add_u64 v[150:151], v[180:181], 0, s[36:37]
	s_mov_b32 m0, s0
	s_nop 0
	global_load_lds_dwordx4 v[150:151], off
	v_lshl_add_u64 v[150:151], v[234:235], 0, s[36:37]
	s_add_i32 m0, s0, 0x2000
	s_nop 0
	global_load_lds_dwordx4 v[150:151], off
	v_lshl_add_u64 v[150:151], v[236:237], 0, s[36:37]
	s_mov_b32 m0, s18
	s_nop 0
	global_load_lds_dwordx4 v[150:151], off
	v_lshl_add_u64 v[150:151], v[238:239], 0, s[36:37]
	s_mov_b32 m0, s28
	s_nop 0
	global_load_lds_dwordx4 v[150:151], off
	s_waitcnt vmcnt(8)
	s_waitcnt lgkmcnt(0)
	s_barrier
	s_setprio 1
	s_waitcnt lgkmcnt(0)
	v_mfma_f32_16x16x32_bf16 v[60:63], v[128:131], v[202:205], v[60:63]
	v_mfma_f32_16x16x32_bf16 v[56:59], v[146:149], v[202:205], v[56:59]
	v_mfma_f32_16x16x32_bf16 v[44:47], v[128:131], v[210:213], v[44:47]
	v_mfma_f32_16x16x32_bf16 v[40:43], v[146:149], v[210:213], v[40:43]
	v_mfma_f32_16x16x32_bf16 v[28:31], v[128:131], v[218:221], v[28:31]
	v_mfma_f32_16x16x32_bf16 v[24:27], v[146:149], v[218:221], v[24:27]
	v_mfma_f32_16x16x32_bf16 v[12:15], v[128:131], v[226:229], v[12:15]
	v_mfma_f32_16x16x32_bf16 v[8:11], v[146:149], v[226:229], v[8:11]
	v_mfma_f32_16x16x32_bf16 v[60:63], v[132:135], v[206:209], v[60:63]
	v_mfma_f32_16x16x32_bf16 v[56:59], v[158:161], v[206:209], v[56:59]
	v_mfma_f32_16x16x32_bf16 v[44:47], v[132:135], v[214:217], v[44:47]
	v_mfma_f32_16x16x32_bf16 v[40:43], v[158:161], v[214:217], v[40:43]
	v_mfma_f32_16x16x32_bf16 v[28:31], v[132:135], v[222:225], v[28:31]
	v_mfma_f32_16x16x32_bf16 v[24:27], v[158:161], v[222:225], v[24:27]
	v_mfma_f32_16x16x32_bf16 v[12:15], v[132:135], v[230:233], v[12:15]
	v_mfma_f32_16x16x32_bf16 v[8:11], v[158:161], v[230:233], v[8:11]
	v_mfma_f32_16x16x32_bf16 v[52:55], v[168:171], v[202:205], v[52:55]
	v_mfma_f32_16x16x32_bf16 v[48:51], v[176:179], v[202:205], v[48:51]
	v_mfma_f32_16x16x32_bf16 v[36:39], v[168:171], v[210:213], v[36:39]
	v_mfma_f32_16x16x32_bf16 v[32:35], v[176:179], v[210:213], v[32:35]
	v_mfma_f32_16x16x32_bf16 v[20:23], v[168:171], v[218:221], v[20:23]
	v_mfma_f32_16x16x32_bf16 v[16:19], v[176:179], v[218:221], v[16:19]
	v_mfma_f32_16x16x32_bf16 v[4:7], v[168:171], v[226:229], v[4:7]
	v_mfma_f32_16x16x32_bf16 v[0:3], v[176:179], v[226:229], v[0:3]
	v_mfma_f32_16x16x32_bf16 v[52:55], v[172:175], v[206:209], v[52:55]
	v_mfma_f32_16x16x32_bf16 v[48:51], v[194:197], v[206:209], v[48:51]
	v_mfma_f32_16x16x32_bf16 v[36:39], v[172:175], v[214:217], v[36:39]
	v_mfma_f32_16x16x32_bf16 v[32:35], v[194:197], v[214:217], v[32:35]
	v_mfma_f32_16x16x32_bf16 v[20:23], v[172:175], v[222:225], v[20:23]
	v_mfma_f32_16x16x32_bf16 v[16:19], v[194:197], v[222:225], v[16:19]
	v_mfma_f32_16x16x32_bf16 v[4:7], v[172:175], v[230:233], v[4:7]
	v_mfma_f32_16x16x32_bf16 v[0:3], v[194:197], v[230:233], v[0:3]
	s_setprio 0
	s_barrier
	s_add_u32 s42, s42, 0x100
	s_addc_u32 s43, s43, 0
	s_add_u32 s44, s44, 0x100
	s_addc_u32 s45, s45, 0
	s_cmp_ge_u32 s47, s31
	s_mov_b32 s0, s47
	s_cbranch_scc0 .LBB0_482
	s_and_b64 vcc, exec, s[66:67]
	s_cbranch_vccz .LBB0_485
	s_barrier
